# E1 + drop redundant acc zeroing pass per unit
# speedup vs baseline: 1.0132x; 1.0102x over previous
.LBB0_310:
	s_ashr_i32 s39, s38, 31
	s_lshl_b64 s[40:41], s[38:39], 19
	s_add_u32 s40, s16, s40
	s_addc_u32 s41, s17, s41
	s_ashr_i32 s37, s36, 31
	s_lshl_b64 s[42:43], s[36:37], 19
	s_add_u32 s42, s18, s42
	v_mov_b32_e32 v103, 0
	v_cmp_lt_i64_e64 s[6:7], s[6:7], v[140:141]
	s_addc_u32 s43, s19, s43
	s_andn2_b64 vcc, exec, s[24:25]
	v_mov_b32_e32 v102, v103
	v_mov_b32_e32 v101, v103
	v_mov_b32_e32 v100, v103
	v_mov_b32_e32 v91, v103
	v_mov_b32_e32 v90, v103
	v_mov_b32_e32 v89, v103
	v_mov_b32_e32 v88, v103
	v_mov_b32_e32 v99, v103
	v_mov_b32_e32 v98, v103
	v_mov_b32_e32 v97, v103
	v_mov_b32_e32 v96, v103
	v_mov_b32_e32 v83, v103
	v_mov_b32_e32 v82, v103
	v_mov_b32_e32 v81, v103
	v_mov_b32_e32 v80, v103
	v_mov_b32_e32 v75, v103
	v_mov_b32_e32 v74, v103
	v_mov_b32_e32 v73, v103
	v_mov_b32_e32 v72, v103
	v_mov_b32_e32 v63, v103
	v_mov_b32_e32 v62, v103
	v_mov_b32_e32 v61, v103
	v_mov_b32_e32 v60, v103
	v_mov_b32_e32 v59, v103
	v_mov_b32_e32 v58, v103
	v_mov_b32_e32 v57, v103
	v_mov_b32_e32 v56, v103
	v_mov_b32_e32 v51, v103
	v_mov_b32_e32 v50, v103
	v_mov_b32_e32 v49, v103
	v_mov_b32_e32 v48, v103
	v_mov_b32_e32 v95, v103
	v_mov_b32_e32 v94, v103
	v_mov_b32_e32 v93, v103
	v_mov_b32_e32 v92, v103
	v_mov_b32_e32 v111, v103
	v_mov_b32_e32 v110, v103
	v_mov_b32_e32 v109, v103
	v_mov_b32_e32 v108, v103
	v_mov_b32_e32 v87, v103
	v_mov_b32_e32 v86, v103
	v_mov_b32_e32 v85, v103
	v_mov_b32_e32 v84, v103
	v_mov_b32_e32 v107, v103
	v_mov_b32_e32 v106, v103
	v_mov_b32_e32 v105, v103
	v_mov_b32_e32 v104, v103
	v_mov_b32_e32 v67, v103
	v_mov_b32_e32 v66, v103
	v_mov_b32_e32 v65, v103
	v_mov_b32_e32 v64, v103
	v_mov_b32_e32 v79, v103
	v_mov_b32_e32 v78, v103
	v_mov_b32_e32 v77, v103
	v_mov_b32_e32 v76, v103
	v_mov_b32_e32 v55, v103
	v_mov_b32_e32 v54, v103
	v_mov_b32_e32 v53, v103
	v_mov_b32_e32 v52, v103
	v_mov_b32_e32 v71, v103
	v_mov_b32_e32 v70, v103
	v_mov_b32_e32 v69, v103
	v_mov_b32_e32 v68, v103
	v_mov_b32_e32 v43, v103
	v_mov_b32_e32 v42, v103
	v_mov_b32_e32 v41, v103
	v_mov_b32_e32 v40, v103
	v_mov_b32_e32 v35, v103
	v_mov_b32_e32 v34, v103
	v_mov_b32_e32 v33, v103
	v_mov_b32_e32 v32, v103
	v_mov_b32_e32 v27, v103
	v_mov_b32_e32 v26, v103
	v_mov_b32_e32 v25, v103
	v_mov_b32_e32 v24, v103
	v_mov_b32_e32 v23, v103
	v_mov_b32_e32 v22, v103
	v_mov_b32_e32 v21, v103
	v_mov_b32_e32 v20, v103
	v_mov_b32_e32 v7, v103
	v_mov_b32_e32 v6, v103
	v_mov_b32_e32 v5, v103
	v_mov_b32_e32 v4, v103
	v_mov_b32_e32 v127, v103
	v_mov_b32_e32 v126, v103
	v_mov_b32_e32 v125, v103
	v_mov_b32_e32 v124, v103
	v_mov_b32_e32 v3, v103
	v_mov_b32_e32 v2, v103
	v_mov_b32_e32 v1, v103
	v_mov_b32_e32 v0, v103
	v_mov_b32_e32 v119, v103
	v_mov_b32_e32 v118, v103
	v_mov_b32_e32 v117, v103
	v_mov_b32_e32 v116, v103
	v_mov_b32_e32 v31, v103
	v_mov_b32_e32 v30, v103
	v_mov_b32_e32 v29, v103
	v_mov_b32_e32 v28, v103
	v_mov_b32_e32 v47, v103
	v_mov_b32_e32 v46, v103
	v_mov_b32_e32 v45, v103
	v_mov_b32_e32 v44, v103
	v_mov_b32_e32 v19, v103
	v_mov_b32_e32 v18, v103
	v_mov_b32_e32 v17, v103
	v_mov_b32_e32 v16, v103
	v_mov_b32_e32 v39, v103
	v_mov_b32_e32 v38, v103
	v_mov_b32_e32 v37, v103
	v_mov_b32_e32 v36, v103
	v_mov_b32_e32 v123, v103
	v_mov_b32_e32 v122, v103
	v_mov_b32_e32 v121, v103
	v_mov_b32_e32 v120, v103
	v_mov_b32_e32 v15, v103
	v_mov_b32_e32 v14, v103
	v_mov_b32_e32 v13, v103
	v_mov_b32_e32 v12, v103
	v_mov_b32_e32 v115, v103
	v_mov_b32_e32 v114, v103
	v_mov_b32_e32 v113, v103
	v_mov_b32_e32 v112, v103
	v_mov_b32_e32 v11, v103
	v_mov_b32_e32 v10, v103
	v_mov_b32_e32 v9, v103
	v_mov_b32_e32 v8, v103
	s_cbranch_vccnz .LBB0_313
	s_and_b64 s[6:7], s[6:7], exec
	s_cselect_b32 s37, s41, s45
	s_cselect_b32 s39, s40, s44
	s_cselect_b32 s51, s43, s47
	s_cselect_b32 s65, s42, s46
	s_add_u32 s66, s46, 0x100
	s_addc_u32 s67, s47, 0
	s_mov_b32 s46, 0

.LBB0_339:
	s_ashr_i32 s47, s46, 31
	s_lshl_b64 s[48:49], s[46:47], 18
	s_add_u32 s48, s2, s48
	s_addc_u32 s49, s3, s49
	s_ashr_i32 s45, s44, 31
	s_lshl_b64 s[50:51], s[44:45], 18
	s_add_u32 s50, s16, s50
	v_cmp_lt_i64_e64 s[6:7], s[6:7], v[138:139]
	s_addc_u32 s51, s17, s51
	s_andn2_b64 vcc, exec, s[34:35]
	s_cbranch_vccz .Lzskip_P2g
	v_mov_b32_e32 v191, 0
	v_mov_b32_e32 v190, v191
	v_mov_b32_e32 v189, v191
	v_mov_b32_e32 v188, v191
	v_mov_b32_e32 v187, v191
	v_mov_b32_e32 v186, v191
	v_mov_b32_e32 v125, v191
	v_mov_b32_e32 v124, v191
	v_mov_b32_e32 v185, v191
	v_mov_b32_e32 v184, v191
	v_mov_b32_e32 v121, v191
	v_mov_b32_e32 v120, v191
	v_mov_b32_e32 v145, v191
	v_mov_b32_e32 v144, v191
	v_mov_b32_e32 v117, v191
	v_mov_b32_e32 v116, v191
	v_mov_b32_e32 v143, v191
	v_mov_b32_e32 v142, v191
	v_mov_b32_e32 v115, v191
	v_mov_b32_e32 v114, v191
	v_mov_b32_e32 v127, v191
	v_mov_b32_e32 v126, v191
	v_mov_b32_e32 v113, v191
	v_mov_b32_e32 v112, v191
	v_mov_b32_e32 v123, v191
	v_mov_b32_e32 v122, v191
	v_mov_b32_e32 v111, v191
	v_mov_b32_e32 v110, v191
	v_mov_b32_e32 v119, v191
	v_mov_b32_e32 v118, v191
	v_mov_b32_e32 v107, v191
	v_mov_b32_e32 v106, v191
	v_mov_b32_e32 v109, v191
	v_mov_b32_e32 v108, v191
	v_mov_b32_e32 v97, v191
	v_mov_b32_e32 v96, v191
	v_mov_b32_e32 v105, v191
	v_mov_b32_e32 v104, v191
	v_mov_b32_e32 v93, v191
	v_mov_b32_e32 v92, v191
	v_mov_b32_e32 v103, v191
	v_mov_b32_e32 v102, v191
	v_mov_b32_e32 v91, v191
	v_mov_b32_e32 v90, v191
	v_mov_b32_e32 v101, v191
	v_mov_b32_e32 v100, v191
	v_mov_b32_e32 v85, v191
	v_mov_b32_e32 v84, v191
	v_mov_b32_e32 v99, v191
	v_mov_b32_e32 v98, v191
	v_mov_b32_e32 v83, v191
	v_mov_b32_e32 v82, v191
	v_mov_b32_e32 v87, v191
	v_mov_b32_e32 v86, v191
	v_mov_b32_e32 v81, v191
	v_mov_b32_e32 v80, v191
	v_mov_b32_e32 v71, v191
	v_mov_b32_e32 v70, v191
	v_mov_b32_e32 v77, v191
	v_mov_b32_e32 v76, v191
	v_mov_b32_e32 v67, v191
	v_mov_b32_e32 v66, v191
	v_mov_b32_e32 v65, v191
	v_mov_b32_e32 v64, v191
	v_mov_b32_e32 v61, v191
	v_mov_b32_e32 v60, v191
	v_mov_b32_e32 v175, v191
	v_mov_b32_e32 v174, v191
	v_mov_b32_e32 v183, v191
	v_mov_b32_e32 v182, v191
	v_mov_b32_e32 v169, v191
	v_mov_b32_e32 v168, v191
	v_mov_b32_e32 v181, v191
	v_mov_b32_e32 v180, v191
	v_mov_b32_e32 v167, v191
	v_mov_b32_e32 v166, v191
	v_mov_b32_e32 v179, v191
	v_mov_b32_e32 v178, v191
	v_mov_b32_e32 v89, v191
	v_mov_b32_e32 v88, v191
	v_mov_b32_e32 v177, v191
	v_mov_b32_e32 v176, v191
	v_mov_b32_e32 v79, v191
	v_mov_b32_e32 v78, v191
	v_mov_b32_e32 v173, v191
	v_mov_b32_e32 v172, v191
	v_mov_b32_e32 v75, v191
	v_mov_b32_e32 v74, v191
	v_mov_b32_e32 v171, v191
	v_mov_b32_e32 v170, v191
	v_mov_b32_e32 v73, v191
	v_mov_b32_e32 v72, v191
	v_mov_b32_e32 v165, v191
	v_mov_b32_e32 v164, v191
	v_mov_b32_e32 v69, v191
	v_mov_b32_e32 v68, v191
	v_mov_b32_e32 v163, v191
	v_mov_b32_e32 v162, v191
	v_mov_b32_e32 v63, v191
	v_mov_b32_e32 v62, v191
	v_mov_b32_e32 v95, v191
	v_mov_b32_e32 v94, v191
	v_mov_b32_e32 v59, v191
	v_mov_b32_e32 v58, v191
	v_mov_b32_e32 v161, v191
	v_mov_b32_e32 v160, v191
	v_mov_b32_e32 v57, v191
	v_mov_b32_e32 v56, v191
	v_mov_b32_e32 v159, v191
	v_mov_b32_e32 v158, v191
	v_mov_b32_e32 v41, v191
	v_mov_b32_e32 v40, v191
	v_mov_b32_e32 v157, v191
	v_mov_b32_e32 v156, v191
	v_mov_b32_e32 v37, v191
	v_mov_b32_e32 v36, v191
	v_mov_b32_e32 v155, v191
	v_mov_b32_e32 v154, v191
	v_mov_b32_e32 v49, v191
	v_mov_b32_e32 v48, v191
	v_mov_b32_e32 v153, v191
	v_mov_b32_e32 v152, v191
	v_mov_b32_e32 v149, v191
	v_mov_b32_e32 v148, v191
	v_mov_b32_e32 v151, v191
	v_mov_b32_e32 v150, v191
	v_mov_b32_e32 v147, v191
	v_mov_b32_e32 v146, v191
	s_cbranch_vccnz .LBB0_343
.Lzskip_P2g:
	s_and_b64 s[6:7], s[6:7], exec
	s_cselect_b32 s45, s49, s57
	s_cselect_b32 s47, s48, s56
	s_cselect_b32 s71, s51, s55
	s_cselect_b32 s72, s50, s54
	s_add_u32 s6, s56, 0x20080
	s_addc_u32 s7, s57, 0
	s_add_u32 s73, s54, 0x100
	s_addc_u32 s74, s55, 0
	s_mov_b32 s54, 0
	v_mov_b32_e32 v0, 0
	v_mov_b32_e32 v1, 0
	v_mov_b32_e32 v2, 0
	v_mov_b32_e32 v3, 0
	v_mov_b32_e32 v4, 0
	v_mov_b32_e32 v5, 0
	v_mov_b32_e32 v6, 0
	v_mov_b32_e32 v7, 0
	v_mov_b32_e32 v8, 0
	v_mov_b32_e32 v9, 0
	v_mov_b32_e32 v10, 0
	v_mov_b32_e32 v11, 0
	v_mov_b32_e32 v12, 0
	v_mov_b32_e32 v13, 0
	v_mov_b32_e32 v14, 0
	v_mov_b32_e32 v15, 0
	v_mov_b32_e32 v16, 0
	v_mov_b32_e32 v17, 0
	v_mov_b32_e32 v18, 0
	v_mov_b32_e32 v19, 0
	v_mov_b32_e32 v20, 0
	v_mov_b32_e32 v21, 0
	v_mov_b32_e32 v22, 0
	v_mov_b32_e32 v23, 0
	v_mov_b32_e32 v24, 0
	v_mov_b32_e32 v25, 0
	v_mov_b32_e32 v26, 0
	v_mov_b32_e32 v27, 0
	v_mov_b32_e32 v28, 0
	v_mov_b32_e32 v29, 0
	v_mov_b32_e32 v30, 0
	v_mov_b32_e32 v31, 0
	v_mov_b32_e32 v32, 0
	v_mov_b32_e32 v33, 0
	v_mov_b32_e32 v34, 0
	v_mov_b32_e32 v35, 0
	v_mov_b32_e32 v36, 0
	v_mov_b32_e32 v37, 0
	v_mov_b32_e32 v38, 0
	v_mov_b32_e32 v39, 0
	v_mov_b32_e32 v40, 0
	v_mov_b32_e32 v41, 0
	v_mov_b32_e32 v42, 0
	v_mov_b32_e32 v43, 0
	v_mov_b32_e32 v44, 0
	v_mov_b32_e32 v45, 0
	v_mov_b32_e32 v46, 0
	v_mov_b32_e32 v47, 0
	v_mov_b32_e32 v48, 0
	v_mov_b32_e32 v49, 0
	v_mov_b32_e32 v50, 0
	v_mov_b32_e32 v51, 0
	v_mov_b32_e32 v52, 0
	v_mov_b32_e32 v53, 0
	v_mov_b32_e32 v54, 0
	v_mov_b32_e32 v55, 0
	v_mov_b32_e32 v56, 0
	v_mov_b32_e32 v57, 0
	v_mov_b32_e32 v58, 0
	v_mov_b32_e32 v59, 0
	v_mov_b32_e32 v60, 0
	v_mov_b32_e32 v61, 0
	v_mov_b32_e32 v62, 0
	v_mov_b32_e32 v63, 0
	v_mov_b32_e32 v64, 0
	v_mov_b32_e32 v65, 0
	v_mov_b32_e32 v66, 0
	v_mov_b32_e32 v67, 0
	v_mov_b32_e32 v68, 0
	v_mov_b32_e32 v69, 0
	v_mov_b32_e32 v70, 0
	v_mov_b32_e32 v71, 0
	v_mov_b32_e32 v72, 0
	v_mov_b32_e32 v73, 0
	v_mov_b32_e32 v74, 0
	v_mov_b32_e32 v75, 0
	v_mov_b32_e32 v76, 0
	v_mov_b32_e32 v77, 0
	v_mov_b32_e32 v78, 0
	v_mov_b32_e32 v79, 0
	v_mov_b32_e32 v80, 0
	v_mov_b32_e32 v81, 0
	v_mov_b32_e32 v82, 0
	v_mov_b32_e32 v83, 0
	v_mov_b32_e32 v84, 0
	v_mov_b32_e32 v85, 0
	v_mov_b32_e32 v86, 0
	v_mov_b32_e32 v87, 0
	v_mov_b32_e32 v88, 0
	v_mov_b32_e32 v89, 0
	v_mov_b32_e32 v90, 0
	v_mov_b32_e32 v91, 0
	v_mov_b32_e32 v92, 0
	v_mov_b32_e32 v93, 0
	v_mov_b32_e32 v94, 0
	v_mov_b32_e32 v95, 0
	v_mov_b32_e32 v96, 0
	v_mov_b32_e32 v97, 0
	v_mov_b32_e32 v98, 0
	v_mov_b32_e32 v99, 0
	v_mov_b32_e32 v100, 0
	v_mov_b32_e32 v101, 0
	v_mov_b32_e32 v102, 0
	v_mov_b32_e32 v103, 0
	v_mov_b32_e32 v104, 0
	v_mov_b32_e32 v105, 0
	v_mov_b32_e32 v106, 0
	v_mov_b32_e32 v107, 0
	v_mov_b32_e32 v108, 0
	v_mov_b32_e32 v109, 0
	v_mov_b32_e32 v110, 0
	v_mov_b32_e32 v111, 0
	v_mov_b32_e32 v112, 0
	v_mov_b32_e32 v113, 0
	v_mov_b32_e32 v114, 0
	v_mov_b32_e32 v115, 0
	v_mov_b32_e32 v116, 0
	v_mov_b32_e32 v117, 0
	v_mov_b32_e32 v118, 0
	v_mov_b32_e32 v119, 0
	v_mov_b32_e32 v120, 0
	v_mov_b32_e32 v121, 0
	v_mov_b32_e32 v122, 0
	v_mov_b32_e32 v123, 0
	v_mov_b32_e32 v124, 0
	v_mov_b32_e32 v125, 0
	v_mov_b32_e32 v126, 0
	v_mov_b32_e32 v127, 0

.LBB0_369:
	s_ashr_i32 s49, s48, 31
	s_lshl_b64 s[20:21], s[48:49], 18
	s_add_u32 s50, s2, s20
	s_addc_u32 s51, s3, s21
	s_ashr_i32 s47, s46, 31
	s_lshl_b64 s[20:21], s[46:47], 18
	s_add_u32 s52, s16, s20
	v_cmp_lt_i64_e64 s[8:9], s[8:9], v[140:141]
	s_addc_u32 s53, s17, s21
	s_andn2_b64 vcc, exec, s[38:39]
	s_cbranch_vccz .Lzskip_P2r
	v_mov_b32_e32 v147, 0
	v_mov_b32_e32 v146, v147
	v_mov_b32_e32 v125, v147
	v_mov_b32_e32 v124, v147
	v_mov_b32_e32 v189, v147
	v_mov_b32_e32 v188, v147
	v_mov_b32_e32 v183, v147
	v_mov_b32_e32 v182, v147
	v_mov_b32_e32 v165, v147
	v_mov_b32_e32 v164, v147
	v_mov_b32_e32 v121, v147
	v_mov_b32_e32 v120, v147
	v_mov_b32_e32 v187, v147
	v_mov_b32_e32 v186, v147
	v_mov_b32_e32 v181, v147
	v_mov_b32_e32 v180, v147
	v_mov_b32_e32 v167, v147
	v_mov_b32_e32 v166, v147
	v_mov_b32_e32 v149, v147
	v_mov_b32_e32 v148, v147
	v_mov_b32_e32 v185, v147
	v_mov_b32_e32 v184, v147
	v_mov_b32_e32 v179, v147
	v_mov_b32_e32 v178, v147
	v_mov_b32_e32 v161, v147
	v_mov_b32_e32 v160, v147
	v_mov_b32_e32 v159, v147
	v_mov_b32_e32 v158, v147
	v_mov_b32_e32 v173, v147
	v_mov_b32_e32 v172, v147
	v_mov_b32_e32 v171, v147
	v_mov_b32_e32 v170, v147
	v_mov_b32_e32 v101, v147
	v_mov_b32_e32 v100, v147
	v_mov_b32_e32 v95, v147
	v_mov_b32_e32 v94, v147
	v_mov_b32_e32 v67, v147
	v_mov_b32_e32 v66, v147
	v_mov_b32_e32 v61, v147
	v_mov_b32_e32 v60, v147
	v_mov_b32_e32 v99, v147
	v_mov_b32_e32 v98, v147
	v_mov_b32_e32 v93, v147
	v_mov_b32_e32 v92, v147
	v_mov_b32_e32 v65, v147
	v_mov_b32_e32 v64, v147
	v_mov_b32_e32 v57, v147
	v_mov_b32_e32 v56, v147
	v_mov_b32_e32 v97, v147
	v_mov_b32_e32 v96, v147
	v_mov_b32_e32 v91, v147
	v_mov_b32_e32 v90, v147
	v_mov_b32_e32 v63, v147
	v_mov_b32_e32 v62, v147
	v_mov_b32_e32 v55, v147
	v_mov_b32_e32 v54, v147
	v_mov_b32_e32 v85, v147
	v_mov_b32_e32 v84, v147
	v_mov_b32_e32 v83, v147
	v_mov_b32_e32 v82, v147
	v_mov_b32_e32 v53, v147
	v_mov_b32_e32 v52, v147
	v_mov_b32_e32 v51, v147
	v_mov_b32_e32 v50, v147
	v_mov_b32_e32 v203, v147
	v_mov_b32_e32 v202, v147
	v_mov_b32_e32 v163, v147
	v_mov_b32_e32 v162, v147
	v_mov_b32_e32 v177, v147
	v_mov_b32_e32 v176, v147
	v_mov_b32_e32 v175, v147
	v_mov_b32_e32 v174, v147
	v_mov_b32_e32 v155, v147
	v_mov_b32_e32 v154, v147
	v_mov_b32_e32 v153, v147
	v_mov_b32_e32 v152, v147
	v_mov_b32_e32 v193, v147
	v_mov_b32_e32 v192, v147
	v_mov_b32_e32 v191, v147
	v_mov_b32_e32 v190, v147
	v_mov_b32_e32 v169, v147
	v_mov_b32_e32 v168, v147
	v_mov_b32_e32 v157, v147
	v_mov_b32_e32 v156, v147
	v_mov_b32_e32 v197, v147
	v_mov_b32_e32 v196, v147
	v_mov_b32_e32 v195, v147
	v_mov_b32_e32 v194, v147
	v_mov_b32_e32 v209, v147
	v_mov_b32_e32 v208, v147
	v_mov_b32_e32 v207, v147
	v_mov_b32_e32 v206, v147
	v_mov_b32_e32 v201, v147
	v_mov_b32_e32 v200, v147
	v_mov_b32_e32 v199, v147
	v_mov_b32_e32 v198, v147
	v_mov_b32_e32 v89, v147
	v_mov_b32_e32 v88, v147
	v_mov_b32_e32 v87, v147
	v_mov_b32_e32 v86, v147
	v_mov_b32_e32 v69, v147
	v_mov_b32_e32 v68, v147
	v_mov_b32_e32 v59, v147
	v_mov_b32_e32 v58, v147
	v_mov_b32_e32 v113, v147
	v_mov_b32_e32 v112, v147
	v_mov_b32_e32 v109, v147
	v_mov_b32_e32 v108, v147
	v_mov_b32_e32 v73, v147
	v_mov_b32_e32 v72, v147
	v_mov_b32_e32 v71, v147
	v_mov_b32_e32 v70, v147
	v_mov_b32_e32 v117, v147
	v_mov_b32_e32 v116, v147
	v_mov_b32_e32 v115, v147
	v_mov_b32_e32 v114, v147
	v_mov_b32_e32 v77, v147
	v_mov_b32_e32 v76, v147
	v_mov_b32_e32 v75, v147
	v_mov_b32_e32 v74, v147
	v_mov_b32_e32 v145, v147
	v_mov_b32_e32 v144, v147
	v_mov_b32_e32 v127, v147
	v_mov_b32_e32 v126, v147
	v_mov_b32_e32 v81, v147
	v_mov_b32_e32 v80, v147
	v_mov_b32_e32 v79, v147
	v_mov_b32_e32 v78, v147
	s_cbranch_vccnz .LBB0_373
.Lzskip_P2r:
	s_and_b64 s[8:9], s[8:9], exec
	s_cselect_b32 s47, s51, s57
	s_cselect_b32 s49, s50, s56
	s_cselect_b32 s73, s53, s59
	s_cselect_b32 s74, s52, s58
	s_add_u32 s75, s58, 0x100
	s_addc_u32 s76, s59, 0
	s_mov_b32 s58, 0
	v_mov_b32_e32 v0, 0
	v_mov_b32_e32 v1, 0
	v_mov_b32_e32 v2, 0
	v_mov_b32_e32 v3, 0
	v_mov_b32_e32 v16, 0
	v_mov_b32_e32 v17, 0
	v_mov_b32_e32 v18, 0
	v_mov_b32_e32 v19, 0
	v_mov_b32_e32 v4, 0
	v_mov_b32_e32 v5, 0
	v_mov_b32_e32 v6, 0
	v_mov_b32_e32 v7, 0
	v_mov_b32_e32 v20, 0
	v_mov_b32_e32 v21, 0
	v_mov_b32_e32 v22, 0
	v_mov_b32_e32 v23, 0
	v_mov_b32_e32 v12, 0
	v_mov_b32_e32 v13, 0
	v_mov_b32_e32 v14, 0
	v_mov_b32_e32 v15, 0
	v_mov_b32_e32 v24, 0
	v_mov_b32_e32 v25, 0
	v_mov_b32_e32 v26, 0
	v_mov_b32_e32 v27, 0
	v_mov_b32_e32 v8, 0
	v_mov_b32_e32 v9, 0
	v_mov_b32_e32 v10, 0
	v_mov_b32_e32 v11, 0
	v_mov_b32_e32 v32, 0
	v_mov_b32_e32 v33, 0
	v_mov_b32_e32 v34, 0
	v_mov_b32_e32 v35, 0
	v_mov_b32_e32 v40, 0
	v_mov_b32_e32 v41, 0
	v_mov_b32_e32 v42, 0
	v_mov_b32_e32 v43, 0
	v_mov_b32_e32 v68, 0
	v_mov_b32_e32 v69, 0
	v_mov_b32_e32 v70, 0
	v_mov_b32_e32 v71, 0
	v_mov_b32_e32 v48, 0
	v_mov_b32_e32 v49, 0
	v_mov_b32_e32 v50, 0
	v_mov_b32_e32 v51, 0
	v_mov_b32_e32 v80, 0
	v_mov_b32_e32 v81, 0
	v_mov_b32_e32 v82, 0
	v_mov_b32_e32 v83, 0
	v_mov_b32_e32 v60, 0
	v_mov_b32_e32 v61, 0
	v_mov_b32_e32 v62, 0
	v_mov_b32_e32 v63, 0
	v_mov_b32_e32 v88, 0
	v_mov_b32_e32 v89, 0
	v_mov_b32_e32 v90, 0
	v_mov_b32_e32 v91, 0
	v_mov_b32_e32 v72, 0
	v_mov_b32_e32 v73, 0
	v_mov_b32_e32 v74, 0
	v_mov_b32_e32 v75, 0
	v_mov_b32_e32 v92, 0
	v_mov_b32_e32 v93, 0
	v_mov_b32_e32 v94, 0
	v_mov_b32_e32 v95, 0
	v_mov_b32_e32 v28, 0
	v_mov_b32_e32 v29, 0
	v_mov_b32_e32 v30, 0
	v_mov_b32_e32 v31, 0
	v_mov_b32_e32 v52, 0
	v_mov_b32_e32 v53, 0
	v_mov_b32_e32 v54, 0
	v_mov_b32_e32 v55, 0
	v_mov_b32_e32 v36, 0
	v_mov_b32_e32 v37, 0
	v_mov_b32_e32 v38, 0
	v_mov_b32_e32 v39, 0
	v_mov_b32_e32 v64, 0
	v_mov_b32_e32 v65, 0
	v_mov_b32_e32 v66, 0
	v_mov_b32_e32 v67, 0
	v_mov_b32_e32 v44, 0
	v_mov_b32_e32 v45, 0
	v_mov_b32_e32 v46, 0
	v_mov_b32_e32 v47, 0
	v_mov_b32_e32 v76, 0
	v_mov_b32_e32 v77, 0
	v_mov_b32_e32 v78, 0
	v_mov_b32_e32 v79, 0
	v_mov_b32_e32 v56, 0
	v_mov_b32_e32 v57, 0
	v_mov_b32_e32 v58, 0
	v_mov_b32_e32 v59, 0
	v_mov_b32_e32 v84, 0
	v_mov_b32_e32 v85, 0
	v_mov_b32_e32 v86, 0
	v_mov_b32_e32 v87, 0
	v_mov_b32_e32 v96, 0
	v_mov_b32_e32 v97, 0
	v_mov_b32_e32 v98, 0
	v_mov_b32_e32 v99, 0
	v_mov_b32_e32 v108, 0
	v_mov_b32_e32 v109, 0
	v_mov_b32_e32 v110, 0
	v_mov_b32_e32 v111, 0
	v_mov_b32_e32 v100, 0
	v_mov_b32_e32 v101, 0
	v_mov_b32_e32 v102, 0
	v_mov_b32_e32 v103, 0
	v_mov_b32_e32 v116, 0
	v_mov_b32_e32 v117, 0
	v_mov_b32_e32 v118, 0
	v_mov_b32_e32 v119, 0
	v_mov_b32_e32 v104, 0
	v_mov_b32_e32 v105, 0
	v_mov_b32_e32 v106, 0
	v_mov_b32_e32 v107, 0
	v_mov_b32_e32 v120, 0
	v_mov_b32_e32 v121, 0
	v_mov_b32_e32 v122, 0
	v_mov_b32_e32 v123, 0
	v_mov_b32_e32 v112, 0
	v_mov_b32_e32 v113, 0
	v_mov_b32_e32 v114, 0
	v_mov_b32_e32 v115, 0
	v_mov_b32_e32 v124, 0
	v_mov_b32_e32 v125, 0
	v_mov_b32_e32 v126, 0
	v_mov_b32_e32 v127, 0

.LBB0_459:
	s_ashr_i32 s53, s52, 31
	s_lshl_b64 s[20:21], s[52:53], 17
	s_add_u32 s58, s90, s20
	v_mov_b32_e32 v139, 0
	s_addc_u32 s59, s91, s21
	s_andn2_b64 vcc, exec, s[44:45]
	v_mov_b32_e32 v138, v139
	v_mov_b32_e32 v137, v139
	v_mov_b32_e32 v136, v139
	v_mov_b32_e32 v127, v139
	v_mov_b32_e32 v126, v139
	v_mov_b32_e32 v125, v139
	v_mov_b32_e32 v124, v139
	v_mov_b32_e32 v119, v139
	v_mov_b32_e32 v118, v139
	v_mov_b32_e32 v117, v139
	v_mov_b32_e32 v116, v139
	v_mov_b32_e32 v107, v139
	v_mov_b32_e32 v106, v139
	v_mov_b32_e32 v105, v139
	v_mov_b32_e32 v104, v139
	v_mov_b32_e32 v99, v139
	v_mov_b32_e32 v98, v139
	v_mov_b32_e32 v97, v139
	v_mov_b32_e32 v96, v139
	v_mov_b32_e32 v87, v139
	v_mov_b32_e32 v86, v139
	v_mov_b32_e32 v85, v139
	v_mov_b32_e32 v84, v139
	v_mov_b32_e32 v79, v139
	v_mov_b32_e32 v78, v139
	v_mov_b32_e32 v77, v139
	v_mov_b32_e32 v76, v139
	v_mov_b32_e32 v71, v139
	v_mov_b32_e32 v70, v139
	v_mov_b32_e32 v69, v139
	v_mov_b32_e32 v68, v139
	v_mov_b32_e32 v131, v139
	v_mov_b32_e32 v130, v139
	v_mov_b32_e32 v129, v139
	v_mov_b32_e32 v128, v139
	v_mov_b32_e32 v123, v139
	v_mov_b32_e32 v122, v139
	v_mov_b32_e32 v121, v139
	v_mov_b32_e32 v120, v139
	v_mov_b32_e32 v111, v139
	v_mov_b32_e32 v110, v139
	v_mov_b32_e32 v109, v139
	v_mov_b32_e32 v108, v139
	v_mov_b32_e32 v103, v139
	v_mov_b32_e32 v102, v139
	v_mov_b32_e32 v101, v139
	v_mov_b32_e32 v100, v139
	v_mov_b32_e32 v91, v139
	v_mov_b32_e32 v90, v139
	v_mov_b32_e32 v89, v139
	v_mov_b32_e32 v88, v139
	v_mov_b32_e32 v83, v139
	v_mov_b32_e32 v82, v139
	v_mov_b32_e32 v81, v139
	v_mov_b32_e32 v80, v139
	v_mov_b32_e32 v75, v139
	v_mov_b32_e32 v74, v139
	v_mov_b32_e32 v73, v139
	v_mov_b32_e32 v72, v139
	v_mov_b32_e32 v67, v139
	v_mov_b32_e32 v66, v139
	v_mov_b32_e32 v65, v139
	v_mov_b32_e32 v64, v139
	v_mov_b32_e32 v63, v139
	v_mov_b32_e32 v62, v139
	v_mov_b32_e32 v61, v139
	v_mov_b32_e32 v60, v139
	v_mov_b32_e32 v55, v139
	v_mov_b32_e32 v54, v139
	v_mov_b32_e32 v53, v139
	v_mov_b32_e32 v52, v139
	v_mov_b32_e32 v47, v139
	v_mov_b32_e32 v46, v139
	v_mov_b32_e32 v45, v139
	v_mov_b32_e32 v44, v139
	v_mov_b32_e32 v39, v139
	v_mov_b32_e32 v38, v139
	v_mov_b32_e32 v37, v139
	v_mov_b32_e32 v36, v139
	v_mov_b32_e32 v31, v139
	v_mov_b32_e32 v30, v139
	v_mov_b32_e32 v29, v139
	v_mov_b32_e32 v28, v139
	v_mov_b32_e32 v23, v139
	v_mov_b32_e32 v22, v139
	v_mov_b32_e32 v21, v139
	v_mov_b32_e32 v20, v139
	v_mov_b32_e32 v15, v139
	v_mov_b32_e32 v14, v139
	v_mov_b32_e32 v13, v139
	v_mov_b32_e32 v12, v139
	v_mov_b32_e32 v7, v139
	v_mov_b32_e32 v6, v139
	v_mov_b32_e32 v5, v139
	v_mov_b32_e32 v4, v139
	v_mov_b32_e32 v59, v139
	v_mov_b32_e32 v58, v139
	v_mov_b32_e32 v57, v139
	v_mov_b32_e32 v56, v139
	v_mov_b32_e32 v51, v139
	v_mov_b32_e32 v50, v139
	v_mov_b32_e32 v49, v139
	v_mov_b32_e32 v48, v139
	v_mov_b32_e32 v43, v139
	v_mov_b32_e32 v42, v139
	v_mov_b32_e32 v41, v139
	v_mov_b32_e32 v40, v139
	v_mov_b32_e32 v35, v139
	v_mov_b32_e32 v34, v139
	v_mov_b32_e32 v33, v139
	v_mov_b32_e32 v32, v139
	v_mov_b32_e32 v27, v139
	v_mov_b32_e32 v26, v139
	v_mov_b32_e32 v25, v139
	v_mov_b32_e32 v24, v139
	v_mov_b32_e32 v19, v139
	v_mov_b32_e32 v18, v139
	v_mov_b32_e32 v17, v139
	v_mov_b32_e32 v16, v139
	v_mov_b32_e32 v11, v139
	v_mov_b32_e32 v10, v139
	v_mov_b32_e32 v9, v139
	v_mov_b32_e32 v8, v139
	v_mov_b32_e32 v3, v139
	v_mov_b32_e32 v2, v139
	v_mov_b32_e32 v1, v139
	v_mov_b32_e32 v0, v139
	s_cbranch_vccnz .LBB0_462
	s_and_b64 s[4:5], s[4:5], exec
	s_cselect_b32 s53, s59, s9
	s_cselect_b32 s55, s58, s8
	s_add_u32 s64, s8, 0x100
	s_addc_u32 s65, s9, 0
	s_mov_b32 s8, 0

.LBB0_603:
	s_ashr_i32 s59, s58, 31
	s_lshl_b64 s[16:17], s[58:59], 19
	s_add_u32 s60, s55, s16
	s_addc_u32 s61, s70, s17
	s_ashr_i32 s57, s56, 31
	s_lshl_b64 s[16:17], s[56:57], 19
	s_add_u32 s62, s71, s16
	v_mov_b32_e32 v159, 0
	v_cmp_lt_i64_e64 s[12:13], s[12:13], v[168:169]
	s_addc_u32 s63, s72, s17
	s_andn2_b64 vcc, exec, s[46:47]
	v_mov_b32_e32 v158, v159
	v_mov_b32_e32 v157, v159
	v_mov_b32_e32 v156, v159
	v_mov_b32_e32 v155, v159
	v_mov_b32_e32 v154, v159
	v_mov_b32_e32 v153, v159
	v_mov_b32_e32 v152, v159
	v_mov_b32_e32 v143, v159
	v_mov_b32_e32 v142, v159
	v_mov_b32_e32 v141, v159
	v_mov_b32_e32 v140, v159
	v_mov_b32_e32 v139, v159
	v_mov_b32_e32 v138, v159
	v_mov_b32_e32 v137, v159
	v_mov_b32_e32 v136, v159
	v_mov_b32_e32 v127, v159
	v_mov_b32_e32 v126, v159
	v_mov_b32_e32 v125, v159
	v_mov_b32_e32 v124, v159
	v_mov_b32_e32 v123, v159
	v_mov_b32_e32 v122, v159
	v_mov_b32_e32 v121, v159
	v_mov_b32_e32 v120, v159
	v_mov_b32_e32 v111, v159
	v_mov_b32_e32 v110, v159
	v_mov_b32_e32 v109, v159
	v_mov_b32_e32 v108, v159
	v_mov_b32_e32 v107, v159
	v_mov_b32_e32 v106, v159
	v_mov_b32_e32 v105, v159
	v_mov_b32_e32 v104, v159
	v_mov_b32_e32 v151, v159
	v_mov_b32_e32 v150, v159
	v_mov_b32_e32 v149, v159
	v_mov_b32_e32 v148, v159
	v_mov_b32_e32 v147, v159
	v_mov_b32_e32 v146, v159
	v_mov_b32_e32 v145, v159
	v_mov_b32_e32 v144, v159
	v_mov_b32_e32 v135, v159
	v_mov_b32_e32 v134, v159
	v_mov_b32_e32 v133, v159
	v_mov_b32_e32 v132, v159
	v_mov_b32_e32 v131, v159
	v_mov_b32_e32 v130, v159
	v_mov_b32_e32 v129, v159
	v_mov_b32_e32 v128, v159
	v_mov_b32_e32 v119, v159
	v_mov_b32_e32 v118, v159
	v_mov_b32_e32 v117, v159
	v_mov_b32_e32 v116, v159
	v_mov_b32_e32 v115, v159
	v_mov_b32_e32 v114, v159
	v_mov_b32_e32 v113, v159
	v_mov_b32_e32 v112, v159
	v_mov_b32_e32 v103, v159
	v_mov_b32_e32 v102, v159
	v_mov_b32_e32 v101, v159
	v_mov_b32_e32 v100, v159
	v_mov_b32_e32 v99, v159
	v_mov_b32_e32 v98, v159
	v_mov_b32_e32 v97, v159
	v_mov_b32_e32 v96, v159
	v_mov_b32_e32 v79, v159
	v_mov_b32_e32 v78, v159
	v_mov_b32_e32 v77, v159
	v_mov_b32_e32 v76, v159
	v_mov_b32_e32 v75, v159
	v_mov_b32_e32 v74, v159
	v_mov_b32_e32 v73, v159
	v_mov_b32_e32 v72, v159
	v_mov_b32_e32 v63, v159
	v_mov_b32_e32 v62, v159
	v_mov_b32_e32 v61, v159
	v_mov_b32_e32 v60, v159
	v_mov_b32_e32 v59, v159
	v_mov_b32_e32 v58, v159
	v_mov_b32_e32 v57, v159
	v_mov_b32_e32 v56, v159
	v_mov_b32_e32 v47, v159
	v_mov_b32_e32 v46, v159
	v_mov_b32_e32 v45, v159
	v_mov_b32_e32 v44, v159
	v_mov_b32_e32 v43, v159
	v_mov_b32_e32 v42, v159
	v_mov_b32_e32 v41, v159
	v_mov_b32_e32 v40, v159
	v_mov_b32_e32 v31, v159
	v_mov_b32_e32 v30, v159
	v_mov_b32_e32 v29, v159
	v_mov_b32_e32 v28, v159
	v_mov_b32_e32 v27, v159
	v_mov_b32_e32 v26, v159
	v_mov_b32_e32 v25, v159
	v_mov_b32_e32 v24, v159
	v_mov_b32_e32 v71, v159
	v_mov_b32_e32 v70, v159
	v_mov_b32_e32 v69, v159
	v_mov_b32_e32 v68, v159
	v_mov_b32_e32 v67, v159
	v_mov_b32_e32 v66, v159
	v_mov_b32_e32 v65, v159
	v_mov_b32_e32 v64, v159
	v_mov_b32_e32 v55, v159
	v_mov_b32_e32 v54, v159
	v_mov_b32_e32 v53, v159
	v_mov_b32_e32 v52, v159
	v_mov_b32_e32 v51, v159
	v_mov_b32_e32 v50, v159
	v_mov_b32_e32 v49, v159
	v_mov_b32_e32 v48, v159
	v_mov_b32_e32 v39, v159
	v_mov_b32_e32 v38, v159
	v_mov_b32_e32 v37, v159
	v_mov_b32_e32 v36, v159
	v_mov_b32_e32 v35, v159
	v_mov_b32_e32 v34, v159
	v_mov_b32_e32 v33, v159
	v_mov_b32_e32 v32, v159
	v_mov_b32_e32 v23, v159
	v_mov_b32_e32 v22, v159
	v_mov_b32_e32 v21, v159
	v_mov_b32_e32 v20, v159
	v_mov_b32_e32 v19, v159
	v_mov_b32_e32 v18, v159
	v_mov_b32_e32 v17, v159
	v_mov_b32_e32 v16, v159
	s_cbranch_vccnz .LBB0_606
	s_and_b64 s[12:13], s[12:13], exec
	s_cselect_b32 s3, s61, s67
	s_cselect_b32 s15, s60, s66
	s_cselect_b32 s16, s63, s65
	s_cselect_b32 s17, s62, s64
	s_add_u32 s12, s66, 0x40080
	s_addc_u32 s13, s67, 0
	s_add_u32 s18, s64, 0x100
	s_addc_u32 s19, s65, 0
	s_mov_b32 s57, 0

.LBB0_714:
	s_ashr_i32 s35, s34, 31
	s_lshl_b64 s[20:21], s[34:35], 18
	s_add_u32 s36, s2, s20
	s_addc_u32 s37, s3, s21
	s_ashr_i32 s31, s30, 31
	s_lshl_b64 s[20:21], s[30:31], 18
	s_add_u32 s38, s16, s20
	s_addc_u32 s39, s17, s21
	s_and_b64 vcc, exec, s[6:7]
	s_cbranch_vccz .Lzskip_P10
	v_mov_b32_e32 v163, 0
	v_mov_b32_e32 v162, 0
	v_mov_b32_e32 v161, 0
	v_mov_b32_e32 v160, 0
	v_mov_b32_e32 v159, 0
	v_mov_b32_e32 v158, 0
	v_mov_b32_e32 v147, 0
	v_mov_b32_e32 v146, 0
	v_mov_b32_e32 v157, 0
	v_mov_b32_e32 v156, 0
	v_mov_b32_e32 v145, 0
	v_mov_b32_e32 v144, 0
	v_mov_b32_e32 v155, 0
	v_mov_b32_e32 v154, 0
	v_mov_b32_e32 v141, 0
	v_mov_b32_e32 v140, 0
	v_mov_b32_e32 v153, 0
	v_mov_b32_e32 v152, 0
	v_mov_b32_e32 v127, 0
	v_mov_b32_e32 v126, 0
	v_mov_b32_e32 v151, 0
	v_mov_b32_e32 v150, 0
	v_mov_b32_e32 v125, 0
	v_mov_b32_e32 v124, 0
	v_mov_b32_e32 v149, 0
	v_mov_b32_e32 v148, 0
	v_mov_b32_e32 v123, 0
	v_mov_b32_e32 v122, 0
	v_mov_b32_e32 v143, 0
	v_mov_b32_e32 v142, 0
	v_mov_b32_e32 v119, 0
	v_mov_b32_e32 v118, 0
	v_mov_b32_e32 v121, 0
	v_mov_b32_e32 v120, 0
	v_mov_b32_e32 v101, 0
	v_mov_b32_e32 v100, 0
	v_mov_b32_e32 v117, 0
	v_mov_b32_e32 v116, 0
	v_mov_b32_e32 v99, 0
	v_mov_b32_e32 v98, 0
	v_mov_b32_e32 v115, 0
	v_mov_b32_e32 v114, 0
	v_mov_b32_e32 v97, 0
	v_mov_b32_e32 v96, 0
	v_mov_b32_e32 v113, 0
	v_mov_b32_e32 v112, 0
	v_mov_b32_e32 v95, 0
	v_mov_b32_e32 v94, 0
	v_mov_b32_e32 v111, 0
	v_mov_b32_e32 v110, 0
	v_mov_b32_e32 v93, 0
	v_mov_b32_e32 v92, 0
	v_mov_b32_e32 v109, 0
	v_mov_b32_e32 v108, 0
	v_mov_b32_e32 v91, 0
	v_mov_b32_e32 v90, 0
	v_mov_b32_e32 v107, 0
	v_mov_b32_e32 v106, 0
	v_mov_b32_e32 v89, 0
	v_mov_b32_e32 v88, 0
	v_mov_b32_e32 v105, 0
	v_mov_b32_e32 v104, 0
	v_mov_b32_e32 v87, 0
	v_mov_b32_e32 v86, 0
	v_mov_b32_e32 v103, 0
	v_mov_b32_e32 v102, 0
	v_mov_b32_e32 v85, 0
	v_mov_b32_e32 v84, 0
	v_mov_b32_e32 v83, 0
	v_mov_b32_e32 v82, 0
	v_mov_b32_e32 v73, 0
	v_mov_b32_e32 v72, 0
	v_mov_b32_e32 v81, 0
	v_mov_b32_e32 v80, 0
	v_mov_b32_e32 v71, 0
	v_mov_b32_e32 v70, 0
	v_mov_b32_e32 v79, 0
	v_mov_b32_e32 v78, 0
	v_mov_b32_e32 v53, 0
	v_mov_b32_e32 v52, 0
	v_mov_b32_e32 v47, 0
	v_mov_b32_e32 v46, 0
	v_mov_b32_e32 v49, 0
	v_mov_b32_e32 v48, 0
	v_mov_b32_e32 v77, 0
	v_mov_b32_e32 v76, 0
	v_mov_b32_e32 v45, 0
	v_mov_b32_e32 v44, 0
	v_mov_b32_e32 v75, 0
	v_mov_b32_e32 v74, 0
	v_mov_b32_e32 v43, 0
	v_mov_b32_e32 v42, 0
	v_mov_b32_e32 v69, 0
	v_mov_b32_e32 v68, 0
	v_mov_b32_e32 v41, 0
	v_mov_b32_e32 v40, 0
	v_mov_b32_e32 v67, 0
	v_mov_b32_e32 v66, 0
	v_mov_b32_e32 v39, 0
	v_mov_b32_e32 v38, 0
	v_mov_b32_e32 v65, 0
	v_mov_b32_e32 v64, 0
	v_mov_b32_e32 v37, 0
	v_mov_b32_e32 v36, 0
	v_mov_b32_e32 v63, 0
	v_mov_b32_e32 v62, 0
	v_mov_b32_e32 v35, 0
	v_mov_b32_e32 v34, 0
	v_mov_b32_e32 v61, 0
	v_mov_b32_e32 v60, 0
	v_mov_b32_e32 v33, 0
	v_mov_b32_e32 v32, 0
	v_mov_b32_e32 v59, 0
	v_mov_b32_e32 v58, 0
	v_mov_b32_e32 v31, 0
	v_mov_b32_e32 v30, 0
	v_mov_b32_e32 v57, 0
	v_mov_b32_e32 v56, 0
	v_mov_b32_e32 v29, 0
	v_mov_b32_e32 v28, 0
	v_mov_b32_e32 v55, 0
	v_mov_b32_e32 v54, 0
	v_mov_b32_e32 v27, 0
	v_mov_b32_e32 v26, 0
	v_mov_b32_e32 v51, 0
	v_mov_b32_e32 v50, 0
	v_mov_b32_e32 v25, 0
	v_mov_b32_e32 v24, 0
	s_cbranch_vccnz .LBB0_718
.Lzskip_P10:
	v_cmp_lt_i64_e32 vcc, s[46:47], v[136:137]
	s_and_b64 s[20:21], vcc, exec
	s_cselect_b32 s31, s37, s43
	s_cselect_b32 s35, s36, s42
	s_cselect_b32 s58, s39, s45
	s_cselect_b32 s59, s38, s44
	s_add_u32 s42, s42, 0x20080
	s_addc_u32 s43, s43, 0
	s_add_u32 s60, s44, 0x100
	s_addc_u32 s61, s45, 0
	s_mov_b32 s44, 0
	v_mov_b32_e32 v0, 0
	v_mov_b32_e32 v1, 0
	v_mov_b32_e32 v2, 0
	v_mov_b32_e32 v3, 0
	v_mov_b32_e32 v4, 0
	v_mov_b32_e32 v5, 0
	v_mov_b32_e32 v6, 0
	v_mov_b32_e32 v7, 0
	v_mov_b32_e32 v8, 0
	v_mov_b32_e32 v9, 0
	v_mov_b32_e32 v10, 0
	v_mov_b32_e32 v11, 0
	v_mov_b32_e32 v12, 0
	v_mov_b32_e32 v13, 0
	v_mov_b32_e32 v14, 0
	v_mov_b32_e32 v15, 0
	v_mov_b32_e32 v16, 0
	v_mov_b32_e32 v17, 0
	v_mov_b32_e32 v18, 0
	v_mov_b32_e32 v19, 0
	v_mov_b32_e32 v20, 0
	v_mov_b32_e32 v21, 0
	v_mov_b32_e32 v22, 0
	v_mov_b32_e32 v23, 0
	v_mov_b32_e32 v24, 0
	v_mov_b32_e32 v25, 0
	v_mov_b32_e32 v26, 0
	v_mov_b32_e32 v27, 0
	v_mov_b32_e32 v28, 0
	v_mov_b32_e32 v29, 0
	v_mov_b32_e32 v30, 0
	v_mov_b32_e32 v31, 0
	v_mov_b32_e32 v32, 0
	v_mov_b32_e32 v33, 0
	v_mov_b32_e32 v34, 0
	v_mov_b32_e32 v35, 0
	v_mov_b32_e32 v36, 0
	v_mov_b32_e32 v37, 0
	v_mov_b32_e32 v38, 0
	v_mov_b32_e32 v39, 0
	v_mov_b32_e32 v40, 0
	v_mov_b32_e32 v41, 0
	v_mov_b32_e32 v42, 0
	v_mov_b32_e32 v43, 0
	v_mov_b32_e32 v44, 0
	v_mov_b32_e32 v45, 0
	v_mov_b32_e32 v46, 0
	v_mov_b32_e32 v47, 0
	v_mov_b32_e32 v48, 0
	v_mov_b32_e32 v49, 0
	v_mov_b32_e32 v50, 0
	v_mov_b32_e32 v51, 0
	v_mov_b32_e32 v52, 0
	v_mov_b32_e32 v53, 0
	v_mov_b32_e32 v54, 0
	v_mov_b32_e32 v55, 0
	v_mov_b32_e32 v56, 0
	v_mov_b32_e32 v57, 0
	v_mov_b32_e32 v58, 0
	v_mov_b32_e32 v59, 0
	v_mov_b32_e32 v60, 0
	v_mov_b32_e32 v61, 0
	v_mov_b32_e32 v62, 0
	v_mov_b32_e32 v63, 0
	v_mov_b32_e32 v64, 0
	v_mov_b32_e32 v65, 0
	v_mov_b32_e32 v66, 0
	v_mov_b32_e32 v67, 0
	v_mov_b32_e32 v68, 0
	v_mov_b32_e32 v69, 0
	v_mov_b32_e32 v70, 0
	v_mov_b32_e32 v71, 0
	v_mov_b32_e32 v72, 0
	v_mov_b32_e32 v73, 0
	v_mov_b32_e32 v74, 0
	v_mov_b32_e32 v75, 0
	v_mov_b32_e32 v76, 0
	v_mov_b32_e32 v77, 0
	v_mov_b32_e32 v78, 0
	v_mov_b32_e32 v79, 0
	v_mov_b32_e32 v80, 0
	v_mov_b32_e32 v81, 0
	v_mov_b32_e32 v82, 0
	v_mov_b32_e32 v83, 0
	v_mov_b32_e32 v84, 0
	v_mov_b32_e32 v85, 0
	v_mov_b32_e32 v86, 0
	v_mov_b32_e32 v87, 0
	v_mov_b32_e32 v88, 0
	v_mov_b32_e32 v89, 0
	v_mov_b32_e32 v90, 0
	v_mov_b32_e32 v91, 0
	v_mov_b32_e32 v92, 0
	v_mov_b32_e32 v93, 0
	v_mov_b32_e32 v94, 0
	v_mov_b32_e32 v95, 0
	v_mov_b32_e32 v96, 0
	v_mov_b32_e32 v97, 0
	v_mov_b32_e32 v98, 0
	v_mov_b32_e32 v99, 0
	v_mov_b32_e32 v100, 0
	v_mov_b32_e32 v101, 0
	v_mov_b32_e32 v102, 0
	v_mov_b32_e32 v103, 0
	v_mov_b32_e32 v104, 0
	v_mov_b32_e32 v105, 0
	v_mov_b32_e32 v106, 0
	v_mov_b32_e32 v107, 0
	v_mov_b32_e32 v108, 0
	v_mov_b32_e32 v109, 0
	v_mov_b32_e32 v110, 0
	v_mov_b32_e32 v111, 0
	v_mov_b32_e32 v112, 0
	v_mov_b32_e32 v113, 0
	v_mov_b32_e32 v114, 0
	v_mov_b32_e32 v115, 0
	v_mov_b32_e32 v116, 0
	v_mov_b32_e32 v117, 0
	v_mov_b32_e32 v118, 0
	v_mov_b32_e32 v119, 0
	v_mov_b32_e32 v120, 0
	v_mov_b32_e32 v121, 0
	v_mov_b32_e32 v122, 0
	v_mov_b32_e32 v123, 0
	v_mov_b32_e32 v124, 0
	v_mov_b32_e32 v125, 0
	v_mov_b32_e32 v126, 0
	v_mov_b32_e32 v127, 0

.LBB0_796:
	v_mov_b32_e32 v139, 0
	s_andn2_b64 vcc, exec, s[38:39]
	v_mov_b32_e32 v138, v139
	v_mov_b32_e32 v137, v139
	v_mov_b32_e32 v136, v139
	v_mov_b32_e32 v143, v139
	v_mov_b32_e32 v142, v139
	v_mov_b32_e32 v141, v139
	v_mov_b32_e32 v140, v139
	v_mov_b32_e32 v127, v139
	v_mov_b32_e32 v126, v139
	v_mov_b32_e32 v125, v139
	v_mov_b32_e32 v124, v139
	v_mov_b32_e32 v123, v139
	v_mov_b32_e32 v122, v139
	v_mov_b32_e32 v121, v139
	v_mov_b32_e32 v120, v139
	v_mov_b32_e32 v111, v139
	v_mov_b32_e32 v110, v139
	v_mov_b32_e32 v109, v139
	v_mov_b32_e32 v108, v139
	v_mov_b32_e32 v107, v139
	v_mov_b32_e32 v106, v139
	v_mov_b32_e32 v105, v139
	v_mov_b32_e32 v104, v139
	v_mov_b32_e32 v95, v139
	v_mov_b32_e32 v94, v139
	v_mov_b32_e32 v93, v139
	v_mov_b32_e32 v92, v139
	v_mov_b32_e32 v91, v139
	v_mov_b32_e32 v90, v139
	v_mov_b32_e32 v89, v139
	v_mov_b32_e32 v88, v139
	v_mov_b32_e32 v135, v139
	v_mov_b32_e32 v134, v139
	v_mov_b32_e32 v133, v139
	v_mov_b32_e32 v132, v139
	v_mov_b32_e32 v131, v139
	v_mov_b32_e32 v130, v139
	v_mov_b32_e32 v129, v139
	v_mov_b32_e32 v128, v139
	v_mov_b32_e32 v119, v139
	v_mov_b32_e32 v118, v139
	v_mov_b32_e32 v117, v139
	v_mov_b32_e32 v116, v139
	v_mov_b32_e32 v115, v139
	v_mov_b32_e32 v114, v139
	v_mov_b32_e32 v113, v139
	v_mov_b32_e32 v112, v139
	v_mov_b32_e32 v103, v139
	v_mov_b32_e32 v102, v139
	v_mov_b32_e32 v101, v139
	v_mov_b32_e32 v100, v139
	v_mov_b32_e32 v99, v139
	v_mov_b32_e32 v98, v139
	v_mov_b32_e32 v97, v139
	v_mov_b32_e32 v96, v139
	v_mov_b32_e32 v87, v139
	v_mov_b32_e32 v86, v139
	v_mov_b32_e32 v85, v139
	v_mov_b32_e32 v84, v139
	v_mov_b32_e32 v83, v139
	v_mov_b32_e32 v82, v139
	v_mov_b32_e32 v81, v139
	v_mov_b32_e32 v80, v139
	v_mov_b32_e32 v67, v139
	v_mov_b32_e32 v66, v139
	v_mov_b32_e32 v65, v139
	v_mov_b32_e32 v64, v139
	v_mov_b32_e32 v63, v139
	v_mov_b32_e32 v62, v139
	v_mov_b32_e32 v61, v139
	v_mov_b32_e32 v60, v139
	v_mov_b32_e32 v47, v139
	v_mov_b32_e32 v46, v139
	v_mov_b32_e32 v45, v139
	v_mov_b32_e32 v44, v139
	v_mov_b32_e32 v43, v139
	v_mov_b32_e32 v42, v139
	v_mov_b32_e32 v41, v139
	v_mov_b32_e32 v40, v139
	v_mov_b32_e32 v31, v139
	v_mov_b32_e32 v30, v139
	v_mov_b32_e32 v29, v139
	v_mov_b32_e32 v28, v139
	v_mov_b32_e32 v27, v139
	v_mov_b32_e32 v26, v139
	v_mov_b32_e32 v25, v139
	v_mov_b32_e32 v24, v139
	v_mov_b32_e32 v15, v139
	v_mov_b32_e32 v14, v139
	v_mov_b32_e32 v13, v139
	v_mov_b32_e32 v12, v139
	v_mov_b32_e32 v11, v139
	v_mov_b32_e32 v10, v139
	v_mov_b32_e32 v9, v139
	v_mov_b32_e32 v8, v139
	v_mov_b32_e32 v55, v139
	v_mov_b32_e32 v54, v139
	v_mov_b32_e32 v53, v139
	v_mov_b32_e32 v52, v139
	v_mov_b32_e32 v51, v139
	v_mov_b32_e32 v50, v139
	v_mov_b32_e32 v49, v139
	v_mov_b32_e32 v48, v139
	v_mov_b32_e32 v39, v139
	v_mov_b32_e32 v38, v139
	v_mov_b32_e32 v37, v139
	v_mov_b32_e32 v36, v139
	v_mov_b32_e32 v35, v139
	v_mov_b32_e32 v34, v139
	v_mov_b32_e32 v33, v139
	v_mov_b32_e32 v32, v139
	v_mov_b32_e32 v23, v139
	v_mov_b32_e32 v22, v139
	v_mov_b32_e32 v21, v139
	v_mov_b32_e32 v20, v139
	v_mov_b32_e32 v19, v139
	v_mov_b32_e32 v18, v139
	v_mov_b32_e32 v17, v139
	v_mov_b32_e32 v16, v139
	v_mov_b32_e32 v7, v139
	v_mov_b32_e32 v6, v139
	v_mov_b32_e32 v5, v139
	v_mov_b32_e32 v4, v139
	v_mov_b32_e32 v3, v139
	v_mov_b32_e32 v2, v139
	v_mov_b32_e32 v1, v139
	v_mov_b32_e32 v0, v139
	s_cbranch_vccnz .LBB0_799
	s_add_u32 s14, s12, 0x100
	s_addc_u32 s15, s13, 0
	s_mov_b32 s8, 0
